# past sub-tile loop: all four kk=0 K fragments of the next sub-tile prefetched from LDS
# baseline (speedup 1.0000x reference)
.LBB0_258:
	v_mov_b32_e32 v16, v143
	v_add_u32_e32 v143, 8, v16
	v_cmp_lt_i32_e32 vcc, v143, v135
	s_mov_b64 s[28:29], s[20:21]
	v_mov_b32_e32 v161, v141
	v_cndmask_b32_e32 v16, v16, v143, vcc
	v_lshl_or_b32 v18, v16, 5, v146
	v_cmp_lt_i32_e64 s[20:21], v18, v133
	s_mov_b64 s[26:27], s[24:25]
	v_mov_b32_e32 v151, v149
	v_cndmask_b32_e64 v16, 0, v18, s[20:21]
	v_ashrrev_i32_e32 v17, 31, v16
	v_lshl_add_u64 v[16:17], v[16:17], 1, s[18:19]
	global_load_ushort v141, v[16:17], off
	v_or_b32_e32 v16, 16, v18
	v_cmp_lt_i32_e64 s[24:25], v16, v133
	v_mov_b32_e32 v162, v137
	v_mov_b32_e32 v160, v139
	v_cndmask_b32_e64 v16, 0, v16, s[24:25]
	v_ashrrev_i32_e32 v17, 31, v16
	v_lshl_add_u64 v[16:17], v[16:17], 1, s[18:19]
	global_load_ushort v149, v[16:17], off
	s_waitcnt vmcnt(14)
	v_mov_b64_e32 v[46:47], v[6:7]
	s_waitcnt vmcnt(12)
	v_mov_b64_e32 v[34:35], v[14:15]
	v_mov_b64_e32 v[44:45], v[4:5]
	v_mov_b64_e32 v[32:33], v[12:13]
	v_mov_b64_e32 v[38:39], v[10:11]
	v_mov_b64_e32 v[42:43], v[2:3]
	v_mov_b64_e32 v[36:37], v[8:9]
	v_mov_b64_e32 v[40:41], v[0:1]
	v_cmp_ge_i32_e32 vcc, v143, v135
	v_mov_b32_e32 v158, 0
	s_mov_b32 s0, 0
	s_or_b64 s[22:23], vcc, s[22:23]
	v_mov_b32_e32 v166, 0xf149f2ca
	v_mov_b32_e32 v159, v158
	v_mov_b32_e32 v164, 0xf149f2ca
	v_mov_b32_e32 v60, v158
	v_mov_b32_e32 v61, v158
	v_mov_b32_e32 v62, v158
	v_mov_b32_e32 v63, v158
	v_mov_b32_e32 v56, v158
	v_mov_b32_e32 v57, v158
	v_mov_b32_e32 v58, v158
	v_mov_b32_e32 v59, v158
	v_mov_b32_e32 v52, v158
	v_mov_b32_e32 v53, v158
	v_mov_b32_e32 v54, v158
	v_mov_b32_e32 v55, v158
	v_mov_b32_e32 v48, v158
	v_mov_b32_e32 v49, v158
	v_mov_b32_e32 v50, v158
	v_mov_b32_e32 v51, v158
	v_mov_b32_e32 v28, v158
	v_mov_b32_e32 v29, v158
	v_mov_b32_e32 v30, v158
	v_mov_b32_e32 v31, v158
	v_mov_b32_e32 v24, v158
	v_mov_b32_e32 v25, v158
	v_mov_b32_e32 v26, v158
	v_mov_b32_e32 v27, v158
	v_mov_b32_e32 v20, v158
	v_mov_b32_e32 v21, v158
	v_mov_b32_e32 v22, v158
	v_mov_b32_e32 v23, v158
	v_mov_b32_e32 v16, v158
	v_mov_b32_e32 v17, v158
	v_mov_b32_e32 v18, v158
	v_mov_b32_e32 v19, v158
	v_mov_b32_e32 v116, v125
	ds_read_b128 v[234:237], v116 offset:2304
	ds_read_b128 v[238:241], v116
	ds_read_b128 v[242:245], v116 offset:4608
	ds_read_b128 v[246:249], v116 offset:6912
.LBB0_259:
	ds_read_b128 v[72:75], v116 offset:64
	ds_read_b128 v[100:103], v116 offset:2368
	v_mov_b32_e32 v163, v164
	v_add_u32_e32 v164, s0, v121
	s_waitcnt lgkmcnt(2)
	v_mfma_f32_16x16x32_bf16 v[198:201], v[234:237], v[40:43], 0
	v_mov_b32_e32 v165, v166
	v_add_u32_e32 v166, 0x2000, v164
	v_add_u32_e32 v167, 0x4000, v164
	v_mfma_f32_16x16x32_bf16 v[104:107], v[234:237], v[36:39], 0
	ds_read_b128 v[76:79], v116 offset:4672
	s_addk_i32 s0, 0x80
	s_cmpk_eq_i32 s0, 0x200
	v_mfma_f32_16x16x32_bf16 v[68:71], v[238:241], v[40:43], 0
	v_mfma_f32_16x16x32_bf16 v[64:67], v[238:241], v[36:39], 0
	v_mfma_f32_16x16x32_bf16 v[92:95], v[242:245], v[40:43], 0
	v_mfma_f32_16x16x32_bf16 v[84:87], v[242:245], v[36:39], 0
	ds_read_b128 v[80:83], v116 offset:6976
	v_add_u32_e32 v116, 0x2400, v116
	v_mfma_f32_16x16x32_bf16 v[96:99], v[246:249], v[40:43], 0
	v_mfma_f32_16x16x32_bf16 v[88:91], v[246:249], v[36:39], 0
	s_waitcnt lgkmcnt(3)
	v_mfma_f32_16x16x32_bf16 v[68:71], v[72:75], v[44:47], v[68:71]
	v_mfma_f32_16x16x32_bf16 v[72:75], v[72:75], v[32:35], v[64:67]
	s_waitcnt lgkmcnt(2)
	v_mfma_f32_16x16x32_bf16 v[64:67], v[100:103], v[44:47], v[198:201]
	v_mfma_f32_16x16x32_bf16 v[100:103], v[100:103], v[32:35], v[104:107]
	s_nop 2
	ds_read2_b64 v[104:107], v164 offset1:4
	ds_read2_b64 v[198:201], v164 offset0:8 offset1:12
	v_add_u32_e32 v164, 0x6000, v164
	s_waitcnt lgkmcnt(3)
	v_mfma_f32_16x16x32_bf16 v[92:95], v[76:79], v[44:47], v[92:95]
	v_mfma_f32_16x16x32_bf16 v[76:79], v[76:79], v[32:35], v[84:87]
	s_nop 2
	ds_read2_b64 v[84:87], v166 offset0:32 offset1:36
	ds_read2_b64 v[202:205], v166 offset0:40 offset1:44
	ds_read2_b64 v[206:209], v167 offset0:64 offset1:68
	ds_read2_b64 v[210:213], v167 offset0:72 offset1:76
	ds_read2_b64 v[214:217], v164 offset0:96 offset1:100
	ds_read2_b64 v[218:221], v164 offset0:104 offset1:108
	s_waitcnt lgkmcnt(8)
	v_mfma_f32_16x16x32_bf16 v[96:99], v[80:83], v[44:47], v[96:99]
	v_mfma_f32_16x16x32_bf16 v[80:83], v[80:83], v[32:35], v[88:91]
	s_nop 2
	v_max3_f32 v88, v68, s4, v69
	v_max3_f32 v89, v72, s4, v73
	v_max3_f32 v88, v88, v70, v71
	v_max3_f32 v89, v89, v74, v75
	v_max3_f32 v88, v88, v64, v65
	v_max3_f32 v89, v89, v100, v101
	v_max3_f32 v88, v88, v66, v67
	v_max3_f32 v89, v89, v102, v103
	v_max3_f32 v88, v88, v92, v93
	v_max3_f32 v89, v89, v76, v77
	v_max3_f32 v88, v88, v94, v95
	v_max3_f32 v89, v89, v78, v79
	v_max3_f32 v88, v88, v96, v97
	v_max3_f32 v89, v89, v80, v81
	v_max3_f32 v88, v88, v98, v99
	v_max3_f32 v89, v89, v82, v83
	v_mov_b32_e32 v90, v88
	v_mov_b32_e32 v91, v89
	s_nop 0
	v_permlane16_swap_b32_e32 v90, v88
	v_permlane16_swap_b32_e32 v91, v89
	v_max_f32_e32 v88, v88, v90
	v_max_f32_e32 v89, v89, v91
	v_mov_b32_e32 v90, v88
	v_mov_b32_e32 v91, v89
	s_nop 0
	v_permlane32_swap_b32_e32 v90, v88
	v_permlane32_swap_b32_e32 v91, v89
	v_max3_f32 v164, v163, v89, v91
	v_max3_f32 v166, v165, v88, v90
	v_sub_f32_e32 v89, v163, v164
	v_sub_f32_e32 v88, v165, v166
	v_sub_f32_e32 v68, v68, v166
	v_sub_f32_e32 v90, v72, v164
	v_sub_f32_e32 v69, v69, v166
	v_sub_f32_e32 v91, v73, v164
	v_sub_f32_e32 v70, v70, v166
	v_sub_f32_e32 v163, v74, v164
	v_sub_f32_e32 v71, v71, v166
	v_sub_f32_e32 v165, v75, v164
	v_sub_f32_e32 v64, v64, v166
	v_sub_f32_e32 v100, v100, v164
	v_sub_f32_e32 v65, v65, v166
	v_sub_f32_e32 v101, v101, v164
	v_sub_f32_e32 v66, v66, v166
	v_sub_f32_e32 v102, v102, v164
	v_sub_f32_e32 v67, v67, v166
	v_sub_f32_e32 v103, v103, v164
	v_exp_f32_e32 v73, v89
	v_sub_f32_e32 v167, v92, v166
	v_sub_f32_e32 v179, v76, v164
	v_sub_f32_e32 v178, v93, v166
	v_sub_f32_e32 v185, v77, v164
	v_sub_f32_e32 v187, v78, v164
	v_sub_f32_e32 v222, v79, v164
	v_sub_f32_e32 v224, v80, v164
	v_sub_f32_e32 v225, v81, v164
	v_sub_f32_e32 v227, v82, v164
	v_sub_f32_e32 v228, v83, v164
	v_exp_f32_e32 v72, v88
	v_exp_f32_e32 v74, v68
	v_exp_f32_e32 v75, v90
	v_exp_f32_e32 v76, v69
	v_exp_f32_e32 v77, v91
	v_exp_f32_e32 v78, v70
	v_exp_f32_e32 v79, v163
	v_exp_f32_e32 v80, v71
	v_exp_f32_e32 v81, v165
	v_exp_f32_e32 v82, v64
	v_exp_f32_e32 v83, v100
	v_exp_f32_e32 v88, v65
	v_exp_f32_e32 v89, v101
	v_exp_f32_e32 v90, v66
	v_exp_f32_e32 v91, v102
	v_exp_f32_e32 v92, v67
	v_exp_f32_e32 v93, v103
	v_sub_f32_e32 v186, v94, v166
	v_sub_f32_e32 v226, v98, v166
	v_exp_f32_e32 v98, v186
	v_mov_b32_e32 v186, v73
	v_sub_f32_e32 v95, v95, v166
	v_sub_f32_e32 v223, v96, v166
	v_sub_f32_e32 v97, v97, v166
	v_sub_f32_e32 v99, v99, v166
	v_pk_mul_f32 v[62:63], v[62:63], v[72:73] op_sel_hi:[1,0]
	v_pk_mul_f32 v[60:61], v[60:61], v[72:73] op_sel_hi:[1,0]
	v_pk_mul_f32 v[58:59], v[58:59], v[72:73] op_sel_hi:[1,0]
	v_cvt_pk_bf16_f32 v64, v74, v76
	v_cvt_pk_bf16_f32 v65, v78, v80
	v_cvt_pk_bf16_f32 v66, v82, v88
	v_cvt_pk_bf16_f32 v67, v90, v92
	v_pk_mul_f32 v[56:57], v[56:57], v[72:73] op_sel_hi:[1,0]
	v_cvt_pk_bf16_f32 v68, v75, v77
	v_cvt_pk_bf16_f32 v69, v79, v81
	v_cvt_pk_bf16_f32 v70, v83, v89
	v_cvt_pk_bf16_f32 v71, v91, v93
	v_pk_mul_f32 v[30:31], v[30:31], v[186:187] op_sel_hi:[1,0]
	v_pk_mul_f32 v[28:29], v[28:29], v[186:187] op_sel_hi:[1,0]
	v_pk_mul_f32 v[26:27], v[26:27], v[186:187] op_sel_hi:[1,0]
	v_pk_mul_f32 v[24:25], v[24:25], v[186:187] op_sel_hi:[1,0]
	v_exp_f32_e32 v94, v167
	v_exp_f32_e32 v96, v178
	v_exp_f32_e32 v100, v95
	v_exp_f32_e32 v102, v223
	v_exp_f32_e32 v178, v97
	s_waitcnt lgkmcnt(7)
	v_mfma_f32_16x16x32_bf16 v[60:63], v[104:107], v[64:67], v[60:63]
	v_mul_f32_e64 v54, v54, v72
	v_mul_f32_e64 v55, v55, v72
	v_pk_mul_f32 v[52:53], v[52:53], v[72:73] op_sel_hi:[1,0]
	v_pk_mul_f32 v[50:51], v[50:51], v[72:73] op_sel_hi:[1,0]
	s_waitcnt lgkmcnt(5)
	v_mfma_f32_16x16x32_bf16 v[56:59], v[84:87], v[64:67], v[56:59]
	v_mul_f32_e64 v48, v48, v72
	v_mul_f32_e64 v49, v49, v72
	v_exp_f32_e32 v95, v179
	v_exp_f32_e32 v97, v185
	v_mfma_f32_16x16x32_bf16 v[28:31], v[104:107], v[68:71], v[28:31]
	v_exp_f32_e32 v104, v226
	v_exp_f32_e32 v101, v222
	v_exp_f32_e32 v103, v224
	v_mfma_f32_16x16x32_bf16 v[24:27], v[84:87], v[68:71], v[24:27]
	v_exp_f32_e32 v84, v99
	v_exp_f32_e32 v99, v187
	v_exp_f32_e32 v179, v225
	s_waitcnt lgkmcnt(3)
	v_mfma_f32_16x16x32_bf16 v[52:55], v[206:209], v[64:67], v[52:55]
	v_exp_f32_e32 v105, v227
	v_pk_mul_f32 v[22:23], v[22:23], v[186:187] op_sel_hi:[1,0]
	v_pk_mul_f32 v[20:21], v[20:21], v[186:187] op_sel_hi:[1,0]
	s_waitcnt lgkmcnt(1)
	v_mfma_f32_16x16x32_bf16 v[48:51], v[214:217], v[64:67], v[48:51]
	v_cvt_pk_bf16_f32 v64, v94, v96
	v_cvt_pk_bf16_f32 v65, v98, v100
	v_cvt_pk_bf16_f32 v66, v102, v178
	v_cvt_pk_bf16_f32 v67, v104, v84
	v_pk_mul_f32 v[18:19], v[18:19], v[186:187] op_sel_hi:[1,0]
	v_pk_mul_f32 v[16:17], v[16:17], v[186:187] op_sel_hi:[1,0]
	v_mfma_f32_16x16x32_bf16 v[60:63], v[198:201], v[64:67], v[60:63]
	v_exp_f32_e32 v85, v228
	v_mfma_f32_16x16x32_bf16 v[56:59], v[202:205], v[64:67], v[56:59]
	v_mfma_f32_16x16x32_bf16 v[52:55], v[210:213], v[64:67], v[52:55]
	s_waitcnt lgkmcnt(0)
	v_mfma_f32_16x16x32_bf16 v[48:51], v[218:221], v[64:67], v[48:51]
	ds_read_b128 v[234:237], v116 offset:2304
	ds_read_b128 v[238:241], v116
	ds_read_b128 v[242:245], v116 offset:4608
	ds_read_b128 v[246:249], v116 offset:6912
	v_add_f32_e64 v64, v74, 0
	v_add_f32_e64 v65, v75, 0
	v_pk_add_f32 v[64:65], v[76:77], v[64:65]
	v_mfma_f32_16x16x32_bf16 v[20:23], v[206:209], v[68:71], v[20:23]
	v_add_f32_e64 v64, v78, v64
	v_add_f32_e64 v65, v79, v65
	v_pk_add_f32 v[64:65], v[80:81], v[64:65]
	v_mfma_f32_16x16x32_bf16 v[16:19], v[214:217], v[68:71], v[16:19]
	v_add_f32_e64 v64, v82, v64
	v_add_f32_e64 v65, v83, v65
	v_cvt_pk_bf16_f32 v68, v95, v97
	v_pk_add_f32 v[64:65], v[88:89], v[64:65]
	v_cvt_pk_bf16_f32 v69, v99, v101
	v_pk_add_f32 v[64:65], v[90:91], v[64:65]
	v_cvt_pk_bf16_f32 v70, v103, v179
	v_pk_add_f32 v[64:65], v[92:93], v[64:65]
	v_cvt_pk_bf16_f32 v71, v105, v85
	v_pk_add_f32 v[64:65], v[94:95], v[64:65]
	s_nop 0
	v_pk_add_f32 v[64:65], v[96:97], v[64:65]
	v_mfma_f32_16x16x32_bf16 v[28:31], v[198:201], v[68:71], v[28:31]
	v_add_f32_e64 v64, v98, v64
	v_add_f32_e64 v65, v99, v65
	v_pk_add_f32 v[64:65], v[100:101], v[64:65]
	v_mfma_f32_16x16x32_bf16 v[24:27], v[202:205], v[68:71], v[24:27]
	v_add_f32_e64 v64, v102, v64
	v_add_f32_e64 v65, v103, v65
	v_pk_add_f32 v[64:65], v[178:179], v[64:65]
	v_mfma_f32_16x16x32_bf16 v[20:23], v[210:213], v[68:71], v[20:23]
	v_add_f32_e64 v64, v104, v64
	v_add_f32_e64 v65, v105, v65
	v_pk_add_f32 v[64:65], v[84:85], v[64:65]
	v_mfma_f32_16x16x32_bf16 v[16:19], v[218:221], v[68:71], v[16:19]
	v_mov_b32_e32 v66, v64
	v_mov_b32_e32 v67, v65
	s_nop 0
	v_permlane16_swap_b32_e32 v66, v64
	v_permlane16_swap_b32_e32 v67, v65
	v_pk_add_f32 v[64:65], v[64:65], v[66:67]
	s_nop 0
	v_mov_b32_e32 v66, v64
	v_mov_b32_e32 v67, v65
	s_nop 0
	v_permlane32_swap_b32_e32 v66, v64
	v_permlane32_swap_b32_e32 v67, v65
	v_pk_add_f32 v[64:65], v[64:65], v[66:67]
	s_nop 0
	v_pk_fma_f32 v[158:159], v[158:159], v[72:73], v[64:65]
	s_cmpk_lg_i32 s0, 0x80
	s_cbranch_scc1 .Lpast_qskip
	s_cmp_lg_u64 s[22:23], 0
	s_cbranch_scc1 .Lpast_qskip
	v_mov_b32_e32 v233, 0
	s_waitcnt vmcnt(1)
	v_and_b32_e32 v137, 0xfff, v141
	v_lshlrev_b32_e32 v232, 7, v137
	v_lshl_add_u64 v[4:5], v[156:157], 0, v[232:233]
	global_load_dwordx4 v[0:3], v[4:5], off
	s_nop 0
	global_load_dwordx4 v[4:7], v[4:5], off offset:64
	s_waitcnt vmcnt(2)
	v_and_b32_e32 v139, 0xfff, v149
	v_lshlrev_b32_e32 v232, 7, v139
	v_lshl_add_u64 v[12:13], v[156:157], 0, v[232:233]
	global_load_dwordx4 v[8:11], v[12:13], off
	s_nop 0
	global_load_dwordx4 v[12:15], v[12:13], off offset:64
